# v91 + grid-barrier waiters poll every s_sleep 2 instead of s_sleep 6 (shorter release-detection latency at each of the 14 barriers)
# speedup vs baseline: 1.0097x; 1.0046x over previous
; __device__ __forceinline__ unsigned xb_ld(unsigned* p)              { return __hip_atomic_load(p, __ATOMIC_RELAXED, __HIP_MEMORY_SCOPE_AGENT); }
; __device__ __forceinline__ unsigned xb_add(unsigned* p, unsigned v) { return __hip_atomic_fetch_add(p, v, __ATOMIC_RELAXED, __HIP_MEMORY_SCOPE_AGENT); }
; #define XB_SPIN(cond, bar) do { unsigned _sp = 0; while (cond) { __builtin_amdgcn_s_sleep(6); \
;     if ((++_sp & 255u) == 0u) { if (xb_ld(&(bar)[XB_TMO])) break; if (_sp > XB_SPIN_CAP) { atomicAdd(&(bar)[XB_TMO], 1u); break; } } } } while (0)
; __device__ __forceinline__ void xcd_barrier(const XcdBarrier& b) {
;     ...
;             else XB_SPIN(xb_ld(&bar[XB_TOPGEN]) == tg, bar);
;             __builtin_amdgcn_fence(__ATOMIC_ACQUIRE, "agent");
;             xb_add(&bar[XB_XGEN(b.x)], 1u);
;             asm volatile("s_waitcnt vmcnt(0)" ::: "memory");
;         } else {
;             XB_SPIN(xb_ld(&bar[XB_XGEN(b.x)]) == gen, bar);
.LBB0_304:
	s_and_b32 s3, s2, 0xff
	s_mov_b64 s[16:17], -1
	s_cmp_lg_u32 s3, 0
	s_mov_b64 s[20:21], -1
	s_sleep 2
	s_cbranch_scc0 .LBB0_307
	s_and_b64 vcc, exec, s[20:21]
	s_cbranch_vccz .LBB0_303

; __device__ __forceinline__ unsigned xb_ld(unsigned* p)              { return __hip_atomic_load(p, __ATOMIC_RELAXED, __HIP_MEMORY_SCOPE_AGENT); }
; __device__ __forceinline__ unsigned xb_add(unsigned* p, unsigned v) { return __hip_atomic_fetch_add(p, v, __ATOMIC_RELAXED, __HIP_MEMORY_SCOPE_AGENT); }
; #define XB_SPIN(cond, bar) do { unsigned _sp = 0; while (cond) { __builtin_amdgcn_s_sleep(6); \
;     if ((++_sp & 255u) == 0u) { if (xb_ld(&(bar)[XB_TMO])) break; if (_sp > XB_SPIN_CAP) { atomicAdd(&(bar)[XB_TMO], 1u); break; } } } } while (0)
; __device__ __forceinline__ void xcd_barrier(const XcdBarrier& b) {
;     ...
;             else XB_SPIN(xb_ld(&bar[XB_TOPGEN]) == tg, bar);
;             __builtin_amdgcn_fence(__ATOMIC_ACQUIRE, "agent");
;             xb_add(&bar[XB_XGEN(b.x)], 1u);
;             asm volatile("s_waitcnt vmcnt(0)" ::: "memory");
;         } else {
;             XB_SPIN(xb_ld(&bar[XB_XGEN(b.x)]) == gen, bar);
.LBB0_321:
	s_and_b32 s3, s2, 0xff
	s_cmp_lg_u32 s3, 0
	s_mov_b64 s[20:21], -1
	s_sleep 2
	s_cbranch_scc0 .LBB0_324
	s_mov_b64 s[22:23], -1
	s_and_b64 vcc, exec, s[20:21]
	s_cbranch_vccz .LBB0_320

; __device__ __forceinline__ unsigned xb_ld(unsigned* p)              { return __hip_atomic_load(p, __ATOMIC_RELAXED, __HIP_MEMORY_SCOPE_AGENT); }
; __device__ __forceinline__ unsigned xb_add(unsigned* p, unsigned v) { return __hip_atomic_fetch_add(p, v, __ATOMIC_RELAXED, __HIP_MEMORY_SCOPE_AGENT); }
; #define XB_SPIN(cond, bar) do { unsigned _sp = 0; while (cond) { __builtin_amdgcn_s_sleep(6); \
;     if ((++_sp & 255u) == 0u) { if (xb_ld(&(bar)[XB_TMO])) break; if (_sp > XB_SPIN_CAP) { atomicAdd(&(bar)[XB_TMO], 1u); break; } } } } while (0)
; __device__ __forceinline__ void xcd_barrier(const XcdBarrier& b) {
;     ...
;             else XB_SPIN(xb_ld(&bar[XB_TOPGEN]) == tg, bar);
;             __builtin_amdgcn_fence(__ATOMIC_ACQUIRE, "agent");
;             xb_add(&bar[XB_XGEN(b.x)], 1u);
;             asm volatile("s_waitcnt vmcnt(0)" ::: "memory");
;         } else {
;             XB_SPIN(xb_ld(&bar[XB_XGEN(b.x)]) == gen, bar);
.LBB0_705:
	s_and_b32 s16, s3, 0xff
	s_mov_b64 s[14:15], -1
	s_cmp_lg_u32 s16, 0
	s_mov_b64 s[18:19], -1
	s_sleep 2
	s_cbranch_scc0 .LBB0_708
	s_and_b64 vcc, exec, s[18:19]
	s_cbranch_vccz .LBB0_704

; __device__ __forceinline__ unsigned xb_ld(unsigned* p)              { return __hip_atomic_load(p, __ATOMIC_RELAXED, __HIP_MEMORY_SCOPE_AGENT); }
; __device__ __forceinline__ unsigned xb_add(unsigned* p, unsigned v) { return __hip_atomic_fetch_add(p, v, __ATOMIC_RELAXED, __HIP_MEMORY_SCOPE_AGENT); }
; #define XB_SPIN(cond, bar) do { unsigned _sp = 0; while (cond) { __builtin_amdgcn_s_sleep(6); \
;     if ((++_sp & 255u) == 0u) { if (xb_ld(&(bar)[XB_TMO])) break; if (_sp > XB_SPIN_CAP) { atomicAdd(&(bar)[XB_TMO], 1u); break; } } } } while (0)
; __device__ __forceinline__ void xcd_barrier(const XcdBarrier& b) {
;     ...
;             else XB_SPIN(xb_ld(&bar[XB_TOPGEN]) == tg, bar);
;             __builtin_amdgcn_fence(__ATOMIC_ACQUIRE, "agent");
;             xb_add(&bar[XB_XGEN(b.x)], 1u);
;             asm volatile("s_waitcnt vmcnt(0)" ::: "memory");
;         } else {
;             XB_SPIN(xb_ld(&bar[XB_XGEN(b.x)]) == gen, bar);
.LBB0_1073:
	s_and_b32 s3, s2, 0xff
	s_mov_b64 s[18:19], -1
	s_cmp_lg_u32 s3, 0
	s_mov_b64 s[22:23], -1
	s_sleep 2
	s_cbranch_scc0 .LBB0_1076
	s_and_b64 vcc, exec, s[22:23]
	s_cbranch_vccz .LBB0_1072

; __device__ __forceinline__ unsigned xb_ld(unsigned* p)              { return __hip_atomic_load(p, __ATOMIC_RELAXED, __HIP_MEMORY_SCOPE_AGENT); }
; __device__ __forceinline__ unsigned xb_add(unsigned* p, unsigned v) { return __hip_atomic_fetch_add(p, v, __ATOMIC_RELAXED, __HIP_MEMORY_SCOPE_AGENT); }
; #define XB_SPIN(cond, bar) do { unsigned _sp = 0; while (cond) { __builtin_amdgcn_s_sleep(6); \
;     if ((++_sp & 255u) == 0u) { if (xb_ld(&(bar)[XB_TMO])) break; if (_sp > XB_SPIN_CAP) { atomicAdd(&(bar)[XB_TMO], 1u); break; } } } } while (0)
; __device__ __forceinline__ void xcd_barrier(const XcdBarrier& b) {
;     ...
;             else XB_SPIN(xb_ld(&bar[XB_TOPGEN]) == tg, bar);
;             __builtin_amdgcn_fence(__ATOMIC_ACQUIRE, "agent");
;             xb_add(&bar[XB_XGEN(b.x)], 1u);
;             asm volatile("s_waitcnt vmcnt(0)" ::: "memory");
;         } else {
;             XB_SPIN(xb_ld(&bar[XB_XGEN(b.x)]) == gen, bar);
.LBB0_1090:
	s_and_b32 s3, s2, 0xff
	s_cmp_lg_u32 s3, 0
	s_mov_b64 s[22:23], -1
	s_sleep 2
	s_cbranch_scc0 .LBB0_1093
	s_mov_b64 s[24:25], -1
	s_and_b64 vcc, exec, s[22:23]
	s_cbranch_vccz .LBB0_1089
